# v10 + layer-0 up-projection: WGs 216..255 (5 tiles) start 4 sleeps later (stagger under EA)
# baseline (speedup 1.0000x reference)
; #define PG8_STAGE(bufoff, gbase, voff) do { _Pragma("unroll") for (int _i = 0; _i < 2; ++_i) \
;         __builtin_amdgcn_global_load_lds((const unsigned*)((const char*)(gbase) + (voff)[_i]), (LAS unsigned*)(lds + (bufoff) + ldsw + _i * 8192), 16, 0, 0); } while (0)
; #define PG8_WAIT_V(n) asm volatile("s_waitcnt vmcnt(" #n ")" ::: "memory")
; #define PG8_BAR __builtin_amdgcn_s_barrier()
; __device__ __forceinline__ bool gemm_phase(LAS unsigned char* lds, int l, int sub, int gi, bool dry = false) {
;     ...
;     Unit cur, nxt; int ui = 0;
;     if (!unit_next(g, 0, cur)) return true;
;     f32x4 acc[2][2][4][2];
; #pragma unroll
;     for (int a = 0; a < 2; ++a)
; #pragma unroll
;         for (int b = 0; b < 2; ++b)
; #pragma unroll
;             for (int m = 0; m < 4; ++m)
; #pragma unroll
;                 for (int n = 0; n < 2; ++n) acc[a][b][m][n] = (f32x4){0.f, 0.f, 0.f, 0.f};
;     bf16x8 At[4][2], B0[2][2], B1[2][2];
;     const char* cA = (const char*)g.A + (size_t)cur.pm * tstepA + (size_t)cur.k0 * kstep; const char* cB = (const char*)g.Bt + (size_t)cur.pn * tstepB + (size_t)cur.k0 * kstep;
;     PG8_STAGE(PG8_SB(0, 0), cB, voffB); PG8_STAGE(PG8_SA(0, 0), cA, voffA); PG8_STAGE(PG8_SB(0, 1), cB + hstepB, voffB); PG8_STAGE(PG8_SA(0, 1), cA + hstepA, voffA);
;     if (wr == 1) PG8_BAR;
;     PG8_WAIT_V(4); PG8_BAR;
;     PG8_STAGE(PG8_SB(1, 0), cB + kstep, voffB); PG8_STAGE(PG8_SA(1, 0), cA + kstep, voffA); PG8_STAGE(PG8_SB(1, 1), cB + hstepB + kstep, voffB);
;     PG8_WAIT_V(6); PG8_BAR;
.Lmy_dl0:
	s_cmp_lg_u32 s17, 6
	s_cbranch_scc1 .Lmy_dl1
	s_cmp_lg_u32 s4, 0
	s_cbranch_scc1 .Lmy_dl1
	s_cmp_lt_u32 s26, 216
	s_cbranch_scc1 .Lmy_nodelay
	s_sleep 127
	s_sleep 127
	s_sleep 127
	s_sleep 127
	s_branch .Lmy_nodelay
